# RMS+forget loop: packed-f32 forget-gate dot products (90 vs 213 instructions), batched first transpose-reduce stage
# speedup vs baseline: 1.0094x; 1.0010x over previous
.LBB0_642:
	s_mov_b32 s8, 0x8000
	v_cmp_gt_i32_e64 s[44:45], s8, v142
	v_cmp_lt_i32_e64 s[46:47], s91, v142
	v_add_u32_e32 v152, 0xffff8000, v142
	v_mov_b64_e32 v[154:155], v[142:143]
	s_waitcnt lgkmcnt(0)
	v_mov_b64_e32 v[130:131], v[148:149]
	s_and_saveexec_b64 s[54:55], s[46:47]
	v_mov_b32_e32 v153, v1
	v_lshlrev_b64 v[130:131], 12, v[152:153]
	v_lshl_add_u64 v[130:131], s[48:49], 0, v[130:131]
	v_mov_b32_e32 v154, v142
	v_mov_b32_e32 v155, v1
	s_or_b64 exec, exec, s[54:55]
	v_lshl_add_u64 v[130:131], v[130:131], 0, v[0:1]
	global_load_dwordx4 v[172:175], v[130:131], off
	global_load_dwordx4 v[138:141], v[130:131], off offset:1024
	s_mov_b32 s8, 0x800000
	s_waitcnt vmcnt(1)
	v_pk_mul_f32 v[132:133], v[174:175], v[174:175]
	v_pk_mul_f32 v[134:135], v[172:173], v[172:173]
	s_nop 0
	v_pk_mov_b32 v[136:137], v[134:135], v[132:133] op_sel:[1,0]
	v_mov_b32_e32 v135, v133
	v_pk_add_f32 v[156:157], v[136:137], v[134:135]
	s_waitcnt vmcnt(0)
	v_pk_mul_f32 v[132:133], v[140:141], v[140:141]
	v_pk_mul_f32 v[134:135], v[138:139], v[138:139]
	v_pk_add_f32 v[156:157], v[156:157], v[156:157] op_sel:[0,1] op_sel_hi:[1,0]
	v_pk_mov_b32 v[136:137], v[134:135], v[132:133] op_sel:[1,0]
	v_mov_b32_e32 v135, v133
	v_pk_add_f32 v[158:159], v[136:137], v[134:135]
	global_load_dwordx4 v[134:137], v[130:131], off offset:2048
	s_nop 0
	global_load_dwordx4 v[130:133], v[130:131], off offset:3072
	v_pk_add_f32 v[158:159], v[158:159], v[158:159] op_sel:[0,1] op_sel_hi:[1,0]
	s_waitcnt vmcnt(0)
	v_mul_f32_e32 v151, v130, v130
	v_mul_f32_e32 v153, v131, v131
	v_mov_b32_e32 v157, v151
	v_mov_b32_e32 v159, v153
	v_pk_add_f32 v[156:157], v[156:157], v[158:159]
	v_mul_f32_e32 v158, v135, v135
	v_mul_f32_e32 v176, v132, v132
	v_pk_fma_f32 v[158:159], v[134:135], v[134:135], v[158:159] op_sel_hi:[1,1,0]
	v_mul_f32_e32 v178, v133, v133
	v_mov_b32_e32 v159, v176
	v_mul_f32_e32 v176, v137, v137
	v_pk_fma_f32 v[176:177], v[136:137], v[136:137], v[176:177] op_sel_hi:[1,1,0]
	s_nop 0
	v_mov_b32_e32 v177, v178
	v_pk_add_f32 v[158:159], v[158:159], v[176:177]
	v_lshlrev_b64 v[178:179], 11, v[154:155]
	v_pk_add_f32 v[156:157], v[156:157], v[158:159]
	s_nop 0
	v_add_f32_e32 v151, v156, v157
	ds_bpermute_b32 v153, v160, v151
	s_waitcnt lgkmcnt(0)
	v_add_f32_e32 v151, v151, v153
	ds_bpermute_b32 v153, v161, v151
	s_waitcnt lgkmcnt(0)
	v_add_f32_e32 v151, v151, v153
	ds_bpermute_b32 v153, v162, v151
	s_waitcnt lgkmcnt(0)
	v_add_f32_e32 v151, v151, v153
	ds_bpermute_b32 v153, v163, v151
	s_waitcnt lgkmcnt(0)
	v_add_f32_e32 v151, v151, v153
	ds_bpermute_b32 v153, v164, v151
	s_waitcnt lgkmcnt(0)
	v_add_f32_e32 v151, v151, v153
	ds_bpermute_b32 v153, v165, v151
	s_waitcnt lgkmcnt(0)
	v_add_f32_e32 v151, v151, v153
	v_fmamk_f32 v151, v151, 0x3a800000, v206
	v_cmp_gt_f32_e64 s[46:47], s8, v151
	v_mul_f32_e32 v153, 0x4b800000, v151
	s_nop 0
	v_cndmask_b32_e64 v151, v151, v153, s[46:47]
	v_rsq_f32_e32 v151, v151
	s_nop 0
	v_mul_f32_e32 v153, 0x45800000, v151
	v_cndmask_b32_e64 v176, v151, v153, s[46:47]
	v_pk_mul_f32 v[156:157], v[174:175], v[176:177] op_sel_hi:[1,0]
	v_pk_mul_f32 v[158:159], v[172:173], v[176:177] op_sel_hi:[1,0]
	v_and_b32_sdwa v172, v157, v205 dst_sel:DWORD dst_unused:UNUSED_PAD src0_sel:WORD_1 src1_sel:DWORD
	v_and_b32_sdwa v173, v159, v205 dst_sel:DWORD dst_unused:UNUSED_PAD src0_sel:WORD_1 src1_sel:DWORD
	v_and_b32_sdwa v151, v156, v205 dst_sel:DWORD dst_unused:UNUSED_PAD src0_sel:WORD_1 src1_sel:DWORD
	v_and_b32_sdwa v153, v158, v205 dst_sel:DWORD dst_unused:UNUSED_PAD src0_sel:WORD_1 src1_sel:DWORD
	v_add3_u32 v172, v157, v172, s91
	v_add3_u32 v173, v159, v173, s91
	v_add3_u32 v153, v158, v153, s91
	v_add3_u32 v151, v156, v151, s91
	v_and_b32_e32 v172, 0xffff0000, v172
	v_and_b32_e32 v174, 0xffff0000, v173
	v_or_b32_sdwa v173, v172, v151 dst_sel:DWORD dst_unused:UNUSED_PAD src0_sel:DWORD src1_sel:WORD_1
	v_or_b32_sdwa v172, v174, v153 dst_sel:DWORD dst_unused:UNUSED_PAD src0_sel:DWORD src1_sel:WORD_1
	v_lshl_add_u64 v[174:175], v[146:147], 0, v[178:179]
	v_pk_mul_f32 v[140:141], v[140:141], v[176:177] op_sel_hi:[1,0]
	v_pk_mul_f32 v[138:139], v[138:139], v[176:177] op_sel_hi:[1,0]
	global_store_dwordx2 v[174:175], v[172:173], off
	v_and_b32_sdwa v172, v141, v205 dst_sel:DWORD dst_unused:UNUSED_PAD src0_sel:WORD_1 src1_sel:DWORD
	v_and_b32_sdwa v173, v139, v205 dst_sel:DWORD dst_unused:UNUSED_PAD src0_sel:WORD_1 src1_sel:DWORD
	v_and_b32_sdwa v151, v140, v205 dst_sel:DWORD dst_unused:UNUSED_PAD src0_sel:WORD_1 src1_sel:DWORD
	v_and_b32_sdwa v153, v138, v205 dst_sel:DWORD dst_unused:UNUSED_PAD src0_sel:WORD_1 src1_sel:DWORD
	v_add3_u32 v172, v141, v172, s91
	v_add3_u32 v173, v139, v173, s91
	v_add3_u32 v153, v138, v153, s91
	v_add3_u32 v151, v140, v151, s91
	v_and_b32_e32 v172, 0xffff0000, v172
	v_and_b32_e32 v177, 0xffff0000, v173
	v_or_b32_sdwa v173, v172, v151 dst_sel:DWORD dst_unused:UNUSED_PAD src0_sel:DWORD src1_sel:WORD_1
	v_or_b32_sdwa v172, v177, v153 dst_sel:DWORD dst_unused:UNUSED_PAD src0_sel:DWORD src1_sel:WORD_1
	v_pk_mul_f32 v[136:137], v[136:137], v[176:177] op_sel_hi:[1,0]
	v_pk_mul_f32 v[134:135], v[134:135], v[176:177] op_sel_hi:[1,0]
	global_store_dwordx2 v[174:175], v[172:173], off offset:512
	v_and_b32_sdwa v172, v137, v205 dst_sel:DWORD dst_unused:UNUSED_PAD src0_sel:WORD_1 src1_sel:DWORD
	v_and_b32_sdwa v173, v135, v205 dst_sel:DWORD dst_unused:UNUSED_PAD src0_sel:WORD_1 src1_sel:DWORD
	v_and_b32_sdwa v151, v136, v205 dst_sel:DWORD dst_unused:UNUSED_PAD src0_sel:WORD_1 src1_sel:DWORD
	v_and_b32_sdwa v153, v134, v205 dst_sel:DWORD dst_unused:UNUSED_PAD src0_sel:WORD_1 src1_sel:DWORD
	v_add3_u32 v172, v137, v172, s91
	v_add3_u32 v173, v135, v173, s91
	v_add3_u32 v153, v134, v153, s91
	v_add3_u32 v151, v136, v151, s91
	v_and_b32_e32 v172, 0xffff0000, v172
	v_and_b32_e32 v177, 0xffff0000, v173
	v_or_b32_sdwa v173, v172, v151 dst_sel:DWORD dst_unused:UNUSED_PAD src0_sel:DWORD src1_sel:WORD_1
	v_or_b32_sdwa v172, v177, v153 dst_sel:DWORD dst_unused:UNUSED_PAD src0_sel:DWORD src1_sel:WORD_1
	v_pk_mul_f32 v[132:133], v[132:133], v[176:177] op_sel_hi:[1,0]
	v_pk_mul_f32 v[130:131], v[130:131], v[176:177] op_sel_hi:[1,0]
	global_store_dwordx2 v[174:175], v[172:173], off offset:1024
	v_and_b32_sdwa v172, v133, v205 dst_sel:DWORD dst_unused:UNUSED_PAD src0_sel:WORD_1 src1_sel:DWORD
	v_and_b32_sdwa v173, v131, v205 dst_sel:DWORD dst_unused:UNUSED_PAD src0_sel:WORD_1 src1_sel:DWORD
	v_and_b32_sdwa v151, v132, v205 dst_sel:DWORD dst_unused:UNUSED_PAD src0_sel:WORD_1 src1_sel:DWORD
	v_and_b32_sdwa v153, v130, v205 dst_sel:DWORD dst_unused:UNUSED_PAD src0_sel:WORD_1 src1_sel:DWORD
	v_add3_u32 v172, v133, v172, s91
	v_add3_u32 v173, v131, v173, s91
	v_add3_u32 v153, v130, v153, s91
	v_add3_u32 v151, v132, v151, s91
	v_and_b32_e32 v172, 0xffff0000, v172
	v_and_b32_e32 v176, 0xffff0000, v173
	v_or_b32_sdwa v173, v172, v151 dst_sel:DWORD dst_unused:UNUSED_PAD src0_sel:DWORD src1_sel:WORD_1
	v_or_b32_sdwa v172, v176, v153 dst_sel:DWORD dst_unused:UNUSED_PAD src0_sel:DWORD src1_sel:WORD_1
	global_store_dwordx2 v[174:175], v[172:173], off offset:1536
	v_pk_mul_f32 v[180:181], v[2:3], v[158:159]
	v_pk_mul_f32 v[182:183], v[18:19], v[158:159]
	v_pk_mul_f32 v[184:185], v[34:35], v[158:159]
	v_pk_mul_f32 v[186:187], v[50:51], v[158:159]
	v_pk_fma_f32 v[180:181], v[4:5], v[156:157], v[180:181]
	v_pk_fma_f32 v[182:183], v[20:21], v[156:157], v[182:183]
	v_pk_fma_f32 v[184:185], v[36:37], v[156:157], v[184:185]
	v_pk_fma_f32 v[186:187], v[52:53], v[156:157], v[186:187]
	v_pk_fma_f32 v[180:181], v[6:7], v[138:139], v[180:181]
	v_pk_fma_f32 v[182:183], v[22:23], v[138:139], v[182:183]
	v_pk_fma_f32 v[184:185], v[38:39], v[138:139], v[184:185]
	v_pk_fma_f32 v[186:187], v[54:55], v[138:139], v[186:187]
	v_pk_fma_f32 v[180:181], v[8:9], v[140:141], v[180:181]
	v_pk_fma_f32 v[182:183], v[24:25], v[140:141], v[182:183]
	v_pk_fma_f32 v[184:185], v[40:41], v[140:141], v[184:185]
	v_pk_fma_f32 v[186:187], v[56:57], v[140:141], v[186:187]
	v_pk_fma_f32 v[180:181], v[10:11], v[134:135], v[180:181]
	v_pk_fma_f32 v[182:183], v[26:27], v[134:135], v[182:183]
	v_pk_fma_f32 v[184:185], v[42:43], v[134:135], v[184:185]
	v_pk_fma_f32 v[186:187], v[58:59], v[134:135], v[186:187]
	v_pk_fma_f32 v[180:181], v[12:13], v[136:137], v[180:181]
	v_pk_fma_f32 v[182:183], v[28:29], v[136:137], v[182:183]
	v_pk_fma_f32 v[184:185], v[44:45], v[136:137], v[184:185]
	v_pk_fma_f32 v[186:187], v[60:61], v[136:137], v[186:187]
	v_pk_fma_f32 v[180:181], v[14:15], v[130:131], v[180:181]
	v_pk_fma_f32 v[182:183], v[30:31], v[130:131], v[182:183]
	v_pk_fma_f32 v[184:185], v[46:47], v[130:131], v[184:185]
	v_pk_fma_f32 v[186:187], v[62:63], v[130:131], v[186:187]
	v_pk_fma_f32 v[180:181], v[16:17], v[132:133], v[180:181]
	v_pk_fma_f32 v[182:183], v[32:33], v[132:133], v[182:183]
	v_pk_fma_f32 v[184:185], v[48:49], v[132:133], v[184:185]
	v_pk_fma_f32 v[186:187], v[64:65], v[132:133], v[186:187]
	v_add_f32_e32 v151, v180, v181
	v_add_f32_e32 v153, v182, v183
	v_add_f32_e32 v172, v184, v185
	v_add_f32_e32 v173, v186, v187
	v_pk_mul_f32 v[180:181], v[66:67], v[158:159]
	v_pk_mul_f32 v[182:183], v[82:83], v[158:159]
	v_pk_mul_f32 v[184:185], v[98:99], v[158:159]
	v_pk_mul_f32 v[186:187], v[114:115], v[158:159]
	v_pk_fma_f32 v[180:181], v[68:69], v[156:157], v[180:181]
	v_pk_fma_f32 v[182:183], v[84:85], v[156:157], v[182:183]
	v_pk_fma_f32 v[184:185], v[100:101], v[156:157], v[184:185]
	v_pk_fma_f32 v[186:187], v[116:117], v[156:157], v[186:187]
	v_pk_fma_f32 v[180:181], v[70:71], v[138:139], v[180:181]
	v_pk_fma_f32 v[182:183], v[86:87], v[138:139], v[182:183]
	v_pk_fma_f32 v[184:185], v[102:103], v[138:139], v[184:185]
	v_pk_fma_f32 v[186:187], v[118:119], v[138:139], v[186:187]
	v_pk_fma_f32 v[180:181], v[72:73], v[140:141], v[180:181]
	v_pk_fma_f32 v[182:183], v[88:89], v[140:141], v[182:183]
	v_pk_fma_f32 v[184:185], v[104:105], v[140:141], v[184:185]
	v_pk_fma_f32 v[186:187], v[120:121], v[140:141], v[186:187]
	v_pk_fma_f32 v[180:181], v[74:75], v[134:135], v[180:181]
	v_pk_fma_f32 v[182:183], v[90:91], v[134:135], v[182:183]
	v_pk_fma_f32 v[184:185], v[106:107], v[134:135], v[184:185]
	v_pk_fma_f32 v[186:187], v[122:123], v[134:135], v[186:187]
	v_pk_fma_f32 v[180:181], v[76:77], v[136:137], v[180:181]
	v_pk_fma_f32 v[182:183], v[92:93], v[136:137], v[182:183]
	v_pk_fma_f32 v[184:185], v[108:109], v[136:137], v[184:185]
	v_pk_fma_f32 v[186:187], v[124:125], v[136:137], v[186:187]
	v_pk_fma_f32 v[180:181], v[78:79], v[130:131], v[180:181]
	v_pk_fma_f32 v[182:183], v[94:95], v[130:131], v[182:183]
	v_pk_fma_f32 v[184:185], v[110:111], v[130:131], v[184:185]
	v_pk_fma_f32 v[186:187], v[126:127], v[130:131], v[186:187]
	v_pk_fma_f32 v[180:181], v[80:81], v[132:133], v[180:181]
	v_pk_fma_f32 v[182:183], v[96:97], v[132:133], v[182:183]
	v_pk_fma_f32 v[184:185], v[112:113], v[132:133], v[184:185]
	v_pk_fma_f32 v[186:187], v[128:129], v[132:133], v[186:187]
	v_add_f32_e32 v174, v180, v181
	v_add_f32_e32 v175, v182, v183
	v_add_f32_e32 v176, v184, v185
	v_add_f32_e32 v130, v186, v187
	v_cndmask_b32_e32 v131, v151, v174, vcc
	v_cndmask_b32_e32 v132, v153, v175, vcc
	v_cndmask_b32_e32 v133, v172, v176, vcc
	v_cndmask_b32_e32 v134, v173, v130, vcc
	ds_bpermute_b32 v131, v166, v131
	ds_bpermute_b32 v132, v166, v132
	ds_bpermute_b32 v133, v166, v133
	ds_bpermute_b32 v134, v166, v134
	v_cndmask_b32_e32 v180, v174, v151, vcc
	v_cndmask_b32_e32 v181, v175, v153, vcc
	v_cndmask_b32_e32 v182, v176, v172, vcc
	v_cndmask_b32_e32 v183, v130, v173, vcc
	s_waitcnt lgkmcnt(0)
	v_add_f32_e32 v131, v180, v131
	v_add_f32_e32 v132, v181, v132
	v_add_f32_e32 v133, v182, v133
	v_add_f32_e32 v130, v183, v134
	v_cndmask_b32_e64 v134, v131, v133, s[38:39]
	v_cndmask_b32_e64 v131, v133, v131, s[38:39]
	ds_bpermute_b32 v133, v167, v134
	s_waitcnt lgkmcnt(0)
	v_add_f32_e32 v131, v131, v133
	v_cndmask_b32_e64 v133, v132, v130, s[38:39]
	v_cndmask_b32_e64 v130, v130, v132, s[38:39]
	ds_bpermute_b32 v132, v167, v133
	s_waitcnt lgkmcnt(0)
	v_add_f32_e32 v130, v130, v132
	v_cndmask_b32_e64 v132, v131, v130, s[40:41]
	v_cndmask_b32_e64 v130, v130, v131, s[40:41]
	ds_bpermute_b32 v131, v168, v132
	s_waitcnt lgkmcnt(0)
	v_add_f32_e32 v130, v130, v131
	ds_bpermute_b32 v131, v169, v130
	s_waitcnt lgkmcnt(0)
	v_add_f32_e32 v130, v130, v131
	ds_bpermute_b32 v131, v170, v130
	s_waitcnt lgkmcnt(0)
	v_add_f32_e32 v130, v130, v131
	ds_bpermute_b32 v131, v171, v130
	s_and_saveexec_b64 s[56:57], s[42:43]
	s_cbranch_execz .LBB0_641
	s_waitcnt lgkmcnt(0)
	v_add_f32_e32 v130, v130, v131
	global_load_dword v131, v[144:145], off
	s_waitcnt vmcnt(0)
	v_add_f32_e32 v130, v130, v131
	v_cmp_ngt_f32_e64 s[46:47], 0, v130
	s_and_saveexec_b64 s[8:9], s[46:47]
	s_xor_b64 s[54:55], exec, s[8:9]
	s_cbranch_execz .LBB0_647
	v_mul_f32_e32 v131, 0xbfb8aa3b, v130
	v_rndne_f32_e32 v132, v131
	s_mov_b32 s8, 0xbfb8aa3b
	v_sub_f32_e32 v133, v131, v132
	v_fma_f32 v131, v130, s8, -v131
	v_fmac_f32_e32 v131, 0xb2a5705f, v130
	v_add_f32_e32 v131, v133, v131
	v_cvt_i32_f32_e32 v132, v132
	v_exp_f32_e32 v131, v131
	s_mov_b32 s8, 0x42ce8ed0
	v_cmp_nlt_f32_e64 s[46:47], s8, v130
	s_mov_b32 s8, 0xc2b17218
	v_ldexp_f32 v131, v131, v132
	v_cndmask_b32_e64 v131, 0, v131, s[46:47]
	v_cmp_ngt_f32_e64 s[46:47], s8, v130
	s_mov_b32 s8, 0x3f2aaaab
	s_nop 0
	v_cndmask_b32_e64 v151, v220, v131, s[46:47]
	v_add_f32_e32 v132, 1.0, v151
	v_add_f32_e32 v130, -1.0, v132
	v_sub_f32_e32 v131, v130, v132
	v_add_f32_e32 v131, 1.0, v131
	v_sub_f32_e32 v130, v151, v130
	v_add_f32_e32 v133, v130, v131
	v_frexp_mant_f32_e32 v134, v132
	v_cvt_f64_f32_e32 v[130:131], v132
	v_frexp_exp_i32_f64_e32 v130, v[130:131]
	v_cmp_gt_f32_e64 s[46:47], s8, v134
	s_mov_b32 s8, 0x3f317218
	s_nop 0
	v_subbrev_co_u32_e64 v138, s[46:47], 0, v130, s[46:47]
	v_sub_u32_e32 v130, 0, v138
	v_ldexp_f32 v131, v132, v130
	v_add_f32_e32 v132, -1.0, v131
	v_add_f32_e32 v134, 1.0, v131
	v_ldexp_f32 v130, v133, v130
	v_add_f32_e32 v133, 1.0, v132
	v_add_f32_e32 v135, -1.0, v134
	v_sub_f32_e32 v133, v131, v133
	v_sub_f32_e32 v131, v131, v135
	v_add_f32_e32 v133, v130, v133
	v_add_f32_e32 v130, v130, v131
	v_add_f32_e32 v139, v134, v130
	v_rcp_f32_e32 v141, v139
	v_sub_f32_e32 v131, v134, v139
	v_add_f32_e32 v140, v130, v131
	v_add_f32_e32 v131, v132, v133
	v_mul_f32_e32 v156, v131, v141
	v_sub_f32_e32 v130, v132, v131
	v_mul_f32_e32 v132, v139, v156
	v_fma_f32 v134, v156, v139, -v132
	v_fmac_f32_e32 v134, v156, v140
	v_add_f32_e32 v153, v133, v130
	v_add_f32_e32 v130, v132, v134
	v_sub_f32_e32 v133, v131, v130
	v_pk_add_f32 v[136:137], v[130:131], v[132:133] neg_lo:[0,1] neg_hi:[0,1]
	v_mov_b32_e32 v135, v130
	v_pk_add_f32 v[130:131], v[136:137], v[134:135] neg_lo:[0,1] neg_hi:[0,1]
	s_nop 0
	v_add_f32_e32 v131, v153, v131
	v_add_f32_e32 v130, v130, v131
	v_add_f32_e32 v131, v133, v130
	v_mul_f32_e32 v153, v141, v131
	v_mul_f32_e32 v132, v139, v153
	v_fma_f32 v134, v153, v139, -v132
	v_fmac_f32_e32 v134, v153, v140
	v_sub_f32_e32 v133, v133, v131
	v_add_f32_e32 v139, v130, v133
	v_add_f32_e32 v130, v132, v134
	v_sub_f32_e32 v133, v131, v130
	v_pk_add_f32 v[136:137], v[130:131], v[132:133] neg_lo:[0,1] neg_hi:[0,1]
	v_mov_b32_e32 v135, v130
	v_pk_add_f32 v[130:131], v[136:137], v[134:135] neg_lo:[0,1] neg_hi:[0,1]
	s_nop 0
	v_add_f32_e32 v131, v139, v131
	v_add_f32_e32 v130, v130, v131
	v_add_f32_e32 v131, v156, v153
	v_add_f32_e32 v130, v133, v130
	v_sub_f32_e32 v132, v131, v156
	v_mul_f32_e32 v130, v141, v130
	v_sub_f32_e32 v132, v153, v132
	v_add_f32_e32 v132, v132, v130
	v_add_f32_e32 v134, v131, v132
	v_mul_f32_e32 v135, v134, v134
	v_fmamk_f32 v130, v135, 0x3e9b6dac, v207
	v_fmaak_f32 v197, v135, v130, 0x3f2aaada
	v_cvt_f32_i32_e32 v130, v138
	v_sub_f32_e32 v131, v134, v131
	v_sub_f32_e32 v131, v132, v131
	v_ldexp_f32 v136, v131, 1
	v_mul_f32_e32 v131, v134, v135
	v_ldexp_f32 v133, v134, 1
	v_pk_mul_f32 v[134:135], v[130:131], v[196:197]
	s_nop 0
	v_fma_f32 v132, v130, s8, -v134
	v_fmac_f32_e32 v132, 0xb102e308, v130
	v_pk_add_f32 v[130:131], v[134:135], v[132:133]
	s_mov_b32 s8, 0x7f800000
	v_sub_f32_e32 v133, v131, v133
	v_sub_f32_e32 v133, v135, v133
	v_add_f32_e32 v137, v136, v133
	v_mov_b32_e32 v136, v134
	v_pk_add_f32 v[134:135], v[130:131], v[134:135] neg_lo:[0,1] neg_hi:[0,1]
	v_pk_add_f32 v[138:139], v[130:131], v[136:137]
	v_mov_b32_e32 v133, v130
	v_mov_b32_e32 v135, v139
	v_pk_add_f32 v[140:141], v[132:133], v[134:135] neg_lo:[0,1] neg_hi:[0,1]
	v_pk_add_f32 v[132:133], v[132:133], v[134:135]
	v_mov_b32_e32 v136, v137
	v_pk_add_f32 v[134:135], v[132:133], v[130:131] op_sel:[1,0] op_sel_hi:[0,1] neg_lo:[0,1] neg_hi:[0,1]
	v_pk_add_f32 v[156:157], v[138:139], v[134:135] op_sel_hi:[1,0] neg_lo:[0,1] neg_hi:[0,1]
	v_mov_b32_e32 v138, v139
	v_mov_b32_e32 v139, v133
	v_pk_mov_b32 v[134:135], v[130:131], v[134:135] op_sel:[1,0]
	v_mov_b32_e32 v137, v130
	v_pk_add_f32 v[134:135], v[138:139], v[134:135] neg_lo:[0,1] neg_hi:[0,1]
	v_mov_b32_e32 v156, v140
	v_pk_add_f32 v[130:131], v[136:137], v[134:135] neg_lo:[0,1] neg_hi:[0,1]
	v_mov_b32_e32 v141, v133
	v_pk_add_f32 v[134:135], v[156:157], v[130:131]
	v_cmp_neq_f32_e64 s[46:47], s8, v151
	v_pk_add_f32 v[136:137], v[134:135], v[134:135] op_sel:[0,1] op_sel_hi:[1,0]
	s_mov_b32 s8, 0x33800000
	v_pk_add_f32 v[132:133], v[132:133], v[136:137] op_sel:[1,0] op_sel_hi:[0,1]
	v_mov_b32_e32 v135, v132
	v_pk_add_f32 v[138:139], v[134:135], v[140:141] neg_lo:[0,1] neg_hi:[0,1]
	v_mov_b32_e32 v131, v136
	v_sub_f32_e32 v133, v134, v138
	v_pk_add_f32 v[130:131], v[130:131], v[138:139] neg_lo:[0,1] neg_hi:[0,1]
	v_sub_f32_e32 v133, v140, v133
	v_add_f32_e32 v130, v130, v133
	v_add_f32_e32 v130, v130, v131
	v_add_f32_e32 v130, v132, v130
	v_cndmask_b32_e64 v130, v220, v130, s[46:47]
	v_cmp_lt_f32_e64 s[46:47], |v151|, s8
	s_nop 1
	v_cndmask_b32_e64 v130, v130, v151, s[46:47]
	v_xor_b32_e32 v131, 0x80000000, v130
